# neighbourhood attention: skip rebuilding the per-wave bias table when the previous item of this workgroup was a light item with the same head (table still valid in LDS)
# baseline (speedup 1.0000x reference)
.LBB0_146:
	s_cmpk_gt_i32 s83, 0xff
	s_mov_b64 s[0:1], -1
	s_cbranch_scc0 .LBB0_184
	s_and_b32 s3, s83, 7
	s_or_b32 s0, s3, s59
	s_mulk_i32 s0, 0x744
	s_add_u32 s0, s72, s0
	s_addc_u32 s1, s73, 0
	s_sub_i32 s8, s83, s62
	s_cmpk_lt_i32 s8, 0x100
	s_cbranch_scc1 .Lnbtbl_build
	s_xor_b32 s8, s8, s83
	s_and_b32 s8, s8, 7
	s_cmp_eq_u32 s8, 0
	s_cbranch_scc1 .Lnbtbl_done
.Lnbtbl_build:
	v_mov_b32_e32 v6, 0xf149f2ca
	v_mov_b32_e32 v7, 0xf149f2ca
	v_mov_b32_e32 v8, 0xf149f2ca
	v_mov_b32_e32 v9, 0xf149f2ca
	v_mov_b32_e32 v10, 0xf149f2ca
	v_mov_b32_e32 v11, 0xf149f2ca
	v_mov_b32_e32 v12, 0xf149f2ca
	v_mov_b32_e32 v13, 0xf149f2ca
	s_mov_b64 s[12:13], exec
	v_readlane_b32 s8, v252, 38
	v_readlane_b32 s9, v252, 39
	s_and_b64 s[8:9], s[12:13], s[8:9]
	s_mov_b64 exec, s[8:9]
	s_cbranch_execz .Lnbtbl_ld0
	v_lshl_add_u64 v[2:3], v[148:149], 2, s[0:1]
	global_load_dword v6, v[2:3], off

.Lnbtbl_done:
	s_lshl_b32 s0, s83, 5
	s_and_b32 s0, s0, 0x7fffff00
	s_add_i32 s0, s58, s0
	s_cmp_lt_i32 s0, 0x8000
	s_movk_i32 s1, 0xf800
	s_cselect_b32 s1, s1, 0x7fffe000
	s_cselect_b32 s21, 32, 0x80
	s_and_b32 s14, s1, s0
	s_sub_i32 s0, s0, s14
	s_ashr_i32 s15, s0, 7
	v_readlane_b32 s0, v252, 55
	s_add_i32 s15, s15, s0
	v_readlane_b32 s8, v252, 26
	s_lshl_b32 s0, s15, 1
	s_sub_i32 s12, s14, s8
	s_add_i32 s4, s21, -10
	s_add_i32 s21, s21, -8
	s_add_i32 s8, s0, -3
	s_add_i32 s1, s0, -4
	s_min_i32 s8, s8, s21
	s_min_i32 s4, s1, s4
	s_min_i32 s1, s1, s21
	s_add_i32 s8, s8, 7
	v_readlane_b32 s9, v252, 27
	s_cmp_lt_i32 s15, 2
	v_or_b32_e32 v1, s0, v169
	v_or_b32_e32 v3, s12, v208
	s_cselect_b32 s20, 0, s4
	s_cselect_b32 s8, 7, s8
	s_cselect_b32 s9, 0, s1
	s_add_i32 s13, s3, 12
	v_lshl_add_u32 v194, v1, 6, v3
	v_mov_b64_e32 v[4:5], s[96:97]
	v_mad_i64_i32 v[4:5], s[0:1], v194, s17, v[4:5]
	s_lshl_b32 s4, s13, 7
	v_lshl_add_u64 v[4:5], v[4:5], 0, s[4:5]
	v_lshl_add_u64 v[4:5], v[180:181], 1, v[4:5]
	global_load_dwordx4 v[66:69], v[4:5], off
	global_load_dwordx4 v[70:73], v[4:5], off offset:32
	global_load_dwordx4 v[74:77], v[4:5], off offset:64
	global_load_dwordx4 v[78:81], v[4:5], off offset:96
	s_sub_i32 s1, s9, s20
	s_max_i32 s26, s1, 0
	s_sub_i32 s0, s8, s20
	s_add_i32 s9, s26, s20
	s_min_i32 s0, s0, 9
	s_lshl_b32 s28, s9, 6
	s_sub_i32 s8, s0, s26
	s_add_i32 s0, s28, s12
	s_lshl_b32 s4, s13, 23
	s_cmp_gt_i32 s8, -1
	v_add_u32_e32 v2, s0, v226
	s_cselect_b64 s[0:1], -1, 0
	s_cmp_lt_i32 s8, 0
	v_lshl_add_u64 v[190:191], v[182:183], 0, s[4:5]
	s_cbranch_scc1 .LBB0_165
	v_ashrrev_i32_e32 v3, 31, v2
	v_lshlrev_b64 v[4:5], 8, v[2:3]
	v_lshl_add_u64 v[4:5], v[190:191], 0, v[4:5]
	v_add_co_u32_e32 v6, vcc, 0x1000, v4
	s_nop 1
	v_addc_co_u32_e32 v7, vcc, 0, v5, vcc
	global_load_dwordx4 v[82:85], v[4:5], off
	global_load_dwordx4 v[86:89], v[4:5], off offset:128
	global_load_dwordx4 v[94:97], v[4:5], off offset:2048
	global_load_dwordx4 v[90:93], v[4:5], off offset:2176
	global_load_dwordx4 v[102:105], v[6:7], off
	global_load_dwordx4 v[98:101], v[6:7], off offset:128
	global_load_dwordx4 v[110:113], v[6:7], off offset:2048
	global_load_dwordx4 v[106:109], v[6:7], off offset:2176
